# grid barrier: all waiters poll the global generation word with two polls in flight; per-XCD generation words dropped
# speedup vs baseline: 1.0015x; 1.0015x over previous
.LBB0_114:
	s_waitcnt lgkmcnt(0)
	v_mov_b32_e32 v2, 0x20160
	ds_read2_b32 v[4:5], v2 offset1:1
	ds_read_b32 v6, v2 offset:8
	v_readlane_b32 s100, v254, 8
	v_readlane_b32 s101, v254, 9
	v_mov_b32_e32 v3, 1
	v_mov_b32_e32 v11, 0
	v_mov_b32_e32 v8, s100
	v_mov_b32_e32 v9, s101
	global_atomic_add v10, v[8:9], v3, off sc0
	s_waitcnt lgkmcnt(0)
	v_add_u32_e32 v7, 1, v6
	ds_write_b32 v2, v7 offset:8
	v_mul_lo_u32 v4, v4, v7
	v_mul_lo_u32 v5, v5, v7
	s_waitcnt vmcnt(0)
	buffer_inv sc1
	v_add_u32_e32 v10, 1, v10
	v_cmp_eq_u32_e32 vcc, v10, v4
	s_cbranch_vccz .Lxb1_follow
	buffer_wbl2 sc1
	v_readlane_b32 s100, v254, 12
	v_readlane_b32 s101, v254, 13
	s_nop 1
	v_mov_b32_e32 v8, s100
	v_mov_b32_e32 v9, s101
	s_waitcnt vmcnt(0)
	global_atomic_add v10, v[8:9], v3, off sc0
	v_readlane_b32 s100, v254, 14
	v_readlane_b32 s101, v254, 15
	s_nop 1
	v_mov_b32_e32 v8, s100
	v_mov_b32_e32 v9, s101
	s_waitcnt vmcnt(0)
	v_add_u32_e32 v10, 1, v10
	v_cmp_eq_u32_e32 vcc, v10, v5
	s_cbranch_vccz .Lxb1_wait
	global_atomic_add v[8:9], v3, off
	s_branch .Lxb1_fin

.Lxb1_poll:
	global_load_dword v12, v[8:9], off sc1
	s_waitcnt vmcnt(1)
	v_cmp_ne_u32_e32 vcc, v10, v6
	s_cbranch_vccnz .Lxb1_fin
	global_load_dword v10, v[8:9], off sc1
	s_waitcnt vmcnt(1)
	v_cmp_ne_u32_e32 vcc, v12, v6
	s_cbranch_vccnz .Lxb1_fin
	v_add_u32_e32 v11, 1, v11
	v_and_b32_e32 v13, 0x7f, v11
	v_cmp_eq_u32_e32 vcc, 0, v13
	s_cbranch_vccz .Lxb1_poll
	v_readlane_b32 s100, v253, 6
	v_readlane_b32 s101, v253, 7
	s_nop 1
	v_mov_b32_e32 v14, s100
	v_mov_b32_e32 v15, s101
	global_load_dword v13, v[14:15], off sc1
	s_waitcnt vmcnt(0)
	v_cmp_ne_u32_e32 vcc, 0, v13
	s_cbranch_vccnz .Lxb1_fin
	v_cmp_lt_u32_e32 vcc, 0x20000, v11
	s_cbranch_vccz .Lxb1_wait
	global_atomic_add v[14:15], v3, off

.LBB0_161:
	s_or_b64 exec, exec, s[18:19]
	s_cmp_lt_i32 s51, 3
	s_cbranch_scc1 .LBB0_215
	s_waitcnt vmcnt(0)
	s_barrier
	s_mov_b64 s[4:5], exec
	v_readlane_b32 s0, v253, 0
	v_readlane_b32 s1, v253, 1
	s_and_b64 s[0:1], s[4:5], s[0:1]
	s_mov_b64 exec, s[0:1]
	s_cbranch_execz .LBB0_214
	s_waitcnt lgkmcnt(0)
	v_mov_b32_e32 v2, 0x20160
	ds_read2_b32 v[4:5], v2 offset1:1
	ds_read_b32 v6, v2 offset:8
	v_readlane_b32 s100, v254, 8
	v_readlane_b32 s101, v254, 9
	v_mov_b32_e32 v3, 1
	v_mov_b32_e32 v11, 0
	v_mov_b32_e32 v8, s100
	v_mov_b32_e32 v9, s101
	global_atomic_add v10, v[8:9], v3, off sc0
	s_waitcnt lgkmcnt(0)
	v_add_u32_e32 v7, 1, v6
	ds_write_b32 v2, v7 offset:8
	v_mul_lo_u32 v4, v4, v7
	v_mul_lo_u32 v5, v5, v7
	s_waitcnt vmcnt(0)
	buffer_inv sc1
	v_add_u32_e32 v10, 1, v10
	v_cmp_eq_u32_e32 vcc, v10, v4
	s_cbranch_vccz .Lxb2_follow
	buffer_wbl2 sc1
	v_readlane_b32 s100, v254, 12
	v_readlane_b32 s101, v254, 13
	s_nop 1
	v_mov_b32_e32 v8, s100
	v_mov_b32_e32 v9, s101
	s_waitcnt vmcnt(0)
	global_atomic_add v10, v[8:9], v3, off sc0
	v_readlane_b32 s100, v254, 14
	v_readlane_b32 s101, v254, 15
	s_nop 1
	v_mov_b32_e32 v8, s100
	v_mov_b32_e32 v9, s101
	s_waitcnt vmcnt(0)
	v_add_u32_e32 v10, 1, v10
	v_cmp_eq_u32_e32 vcc, v10, v5
	s_cbranch_vccz .Lxb2_wait
	global_atomic_add v[8:9], v3, off
	s_branch .Lxb2_fin

.LBB0_235:
	s_add_i32 s7, s17, 3
	s_cmp_ge_i32 s7, s51
	s_cbranch_scc1 .LBB0_289
	s_waitcnt vmcnt(0)
	s_waitcnt lgkmcnt(0)
	s_barrier
	s_mov_b64 s[4:5], exec
	v_readlane_b32 s8, v253, 0
	v_readlane_b32 s9, v253, 1
	s_and_b64 s[8:9], s[4:5], s[8:9]
	s_mov_b64 exec, s[8:9]
	s_cbranch_execz .LBB0_288
	s_waitcnt lgkmcnt(0)
	v_mov_b32_e32 v2, 0x20160
	ds_read2_b32 v[4:5], v2 offset1:1
	ds_read_b32 v6, v2 offset:8
	v_readlane_b32 s100, v254, 8
	v_readlane_b32 s101, v254, 9
	v_mov_b32_e32 v3, 1
	v_mov_b32_e32 v11, 0
	v_mov_b32_e32 v8, s100
	v_mov_b32_e32 v9, s101
	global_atomic_add v10, v[8:9], v3, off sc0
	s_waitcnt lgkmcnt(0)
	v_add_u32_e32 v7, 1, v6
	ds_write_b32 v2, v7 offset:8
	v_mul_lo_u32 v4, v4, v7
	v_mul_lo_u32 v5, v5, v7
	s_waitcnt vmcnt(0)
	buffer_inv sc1
	v_add_u32_e32 v10, 1, v10
	v_cmp_eq_u32_e32 vcc, v10, v4
	s_cbranch_vccz .Lxb3_follow
	buffer_wbl2 sc1
	v_readlane_b32 s100, v254, 12
	v_readlane_b32 s101, v254, 13
	s_nop 1
	v_mov_b32_e32 v8, s100
	v_mov_b32_e32 v9, s101
	s_waitcnt vmcnt(0)
	global_atomic_add v10, v[8:9], v3, off sc0
	v_readlane_b32 s100, v254, 14
	v_readlane_b32 s101, v254, 15
	s_nop 1
	v_mov_b32_e32 v8, s100
	v_mov_b32_e32 v9, s101
	s_waitcnt vmcnt(0)
	v_add_u32_e32 v10, 1, v10
	v_cmp_eq_u32_e32 vcc, v10, v5
	s_cbranch_vccz .Lxb3_wait
	global_atomic_add v[8:9], v3, off
	s_branch .Lxb3_fin

.LBB0_308:
	s_add_i32 s7, s17, 4
	s_cmp_ge_i32 s7, s51
	s_cbranch_scc1 .LBB0_362
	s_waitcnt vmcnt(0)
	s_waitcnt vmcnt(0) lgkmcnt(0)
	s_barrier
	s_mov_b64 s[4:5], exec
	v_readlane_b32 s8, v253, 0
	v_readlane_b32 s9, v253, 1
	s_and_b64 s[8:9], s[4:5], s[8:9]
	s_mov_b64 exec, s[8:9]
	s_cbranch_execz .LBB0_361
	s_waitcnt lgkmcnt(0)
	v_mov_b32_e32 v2, 0x20160
	ds_read2_b32 v[4:5], v2 offset1:1
	ds_read_b32 v6, v2 offset:8
	v_readlane_b32 s100, v254, 8
	v_readlane_b32 s101, v254, 9
	v_mov_b32_e32 v3, 1
	v_mov_b32_e32 v11, 0
	v_mov_b32_e32 v8, s100
	v_mov_b32_e32 v9, s101
	global_atomic_add v10, v[8:9], v3, off sc0
	s_waitcnt lgkmcnt(0)
	v_add_u32_e32 v7, 1, v6
	ds_write_b32 v2, v7 offset:8
	v_mul_lo_u32 v4, v4, v7
	v_mul_lo_u32 v5, v5, v7
	s_waitcnt vmcnt(0)
	buffer_inv sc1
	v_add_u32_e32 v10, 1, v10
	v_cmp_eq_u32_e32 vcc, v10, v4
	s_cbranch_vccz .Lxb4_follow
	buffer_wbl2 sc1
	v_readlane_b32 s100, v254, 12
	v_readlane_b32 s101, v254, 13
	s_nop 1
	v_mov_b32_e32 v8, s100
	v_mov_b32_e32 v9, s101
	s_waitcnt vmcnt(0)
	global_atomic_add v10, v[8:9], v3, off sc0
	v_readlane_b32 s100, v254, 14
	v_readlane_b32 s101, v254, 15
	s_nop 1
	v_mov_b32_e32 v8, s100
	v_mov_b32_e32 v9, s101
	s_waitcnt vmcnt(0)
	v_add_u32_e32 v10, 1, v10
	v_cmp_eq_u32_e32 vcc, v10, v5
	s_cbranch_vccz .Lxb4_wait
	global_atomic_add v[8:9], v3, off
	s_branch .Lxb4_fin

.LBB0_388:
	s_add_i32 s6, s17, 5
	s_cmp_ge_i32 s6, s51
	s_cbranch_scc1 .LBB0_442
	s_waitcnt vmcnt(0)
	s_waitcnt vmcnt(0)
	s_barrier
	s_mov_b64 s[4:5], exec
	v_readlane_b32 s8, v253, 0
	v_readlane_b32 s9, v253, 1
	s_and_b64 s[8:9], s[4:5], s[8:9]
	s_mov_b64 exec, s[8:9]
	s_cbranch_execz .LBB0_441
	s_waitcnt lgkmcnt(0)
	v_mov_b32_e32 v2, 0x20160
	ds_read2_b32 v[4:5], v2 offset1:1
	ds_read_b32 v6, v2 offset:8
	v_readlane_b32 s100, v254, 8
	v_readlane_b32 s101, v254, 9
	v_mov_b32_e32 v3, 1
	v_mov_b32_e32 v11, 0
	v_mov_b32_e32 v8, s100
	v_mov_b32_e32 v9, s101
	global_atomic_add v10, v[8:9], v3, off sc0
	s_waitcnt lgkmcnt(0)
	v_add_u32_e32 v7, 1, v6
	ds_write_b32 v2, v7 offset:8
	v_mul_lo_u32 v4, v4, v7
	v_mul_lo_u32 v5, v5, v7
	s_waitcnt vmcnt(0)
	buffer_inv sc1
	v_add_u32_e32 v10, 1, v10
	v_cmp_eq_u32_e32 vcc, v10, v4
	s_cbranch_vccz .Lxb5_follow
	buffer_wbl2 sc1
	v_readlane_b32 s100, v254, 12
	v_readlane_b32 s101, v254, 13
	s_nop 1
	v_mov_b32_e32 v8, s100
	v_mov_b32_e32 v9, s101
	s_waitcnt vmcnt(0)
	global_atomic_add v10, v[8:9], v3, off sc0
	v_readlane_b32 s100, v254, 14
	v_readlane_b32 s101, v254, 15
	s_nop 1
	v_mov_b32_e32 v8, s100
	v_mov_b32_e32 v9, s101
	s_waitcnt vmcnt(0)
	v_add_u32_e32 v10, 1, v10
	v_cmp_eq_u32_e32 vcc, v10, v5
	s_cbranch_vccz .Lxb5_wait
	global_atomic_add v[8:9], v3, off
	s_branch .Lxb5_fin

.LBB0_495:
	s_add_i32 s6, s17, 6
	s_cmp_ge_i32 s6, s51
	s_cbranch_scc1 .LBB0_549
	s_waitcnt vmcnt(0)
	s_waitcnt vmcnt(0)
	s_barrier
	s_mov_b64 s[4:5], exec
	v_readlane_b32 s8, v253, 0
	v_readlane_b32 s9, v253, 1
	s_and_b64 s[8:9], s[4:5], s[8:9]
	s_mov_b64 exec, s[8:9]
	s_cbranch_execz .LBB0_548
	s_waitcnt lgkmcnt(0)
	v_mov_b32_e32 v2, 0x20160
	ds_read2_b32 v[4:5], v2 offset1:1
	ds_read_b32 v6, v2 offset:8
	v_readlane_b32 s100, v254, 8
	v_readlane_b32 s101, v254, 9
	v_mov_b32_e32 v3, 1
	v_mov_b32_e32 v11, 0
	v_mov_b32_e32 v8, s100
	v_mov_b32_e32 v9, s101
	global_atomic_add v10, v[8:9], v3, off sc0
	s_waitcnt lgkmcnt(0)
	v_add_u32_e32 v7, 1, v6
	ds_write_b32 v2, v7 offset:8
	v_mul_lo_u32 v4, v4, v7
	v_mul_lo_u32 v5, v5, v7
	s_waitcnt vmcnt(0)
	buffer_inv sc1
	v_add_u32_e32 v10, 1, v10
	v_cmp_eq_u32_e32 vcc, v10, v4
	s_cbranch_vccz .Lxb6_follow
	buffer_wbl2 sc1
	v_readlane_b32 s100, v254, 12
	v_readlane_b32 s101, v254, 13
	s_nop 1
	v_mov_b32_e32 v8, s100
	v_mov_b32_e32 v9, s101
	s_waitcnt vmcnt(0)
	global_atomic_add v10, v[8:9], v3, off sc0
	v_readlane_b32 s100, v254, 14
	v_readlane_b32 s101, v254, 15
	s_nop 1
	v_mov_b32_e32 v8, s100
	v_mov_b32_e32 v9, s101
	s_waitcnt vmcnt(0)
	v_add_u32_e32 v10, 1, v10
	v_cmp_eq_u32_e32 vcc, v10, v5
	s_cbranch_vccz .Lxb6_wait
	global_atomic_add v[8:9], v3, off
	s_branch .Lxb6_fin

.LBB0_627:
	s_add_i32 s6, s17, 7
	s_cmp_ge_i32 s6, s51
	s_cbranch_scc1 .LBB0_681
	s_waitcnt vmcnt(0)
	s_waitcnt vmcnt(0)
	s_barrier
	s_mov_b64 s[4:5], exec
	v_readlane_b32 s8, v253, 0
	v_readlane_b32 s9, v253, 1
	s_and_b64 s[8:9], s[4:5], s[8:9]
	s_mov_b64 exec, s[8:9]
	s_cbranch_execz .LBB0_680
	s_waitcnt lgkmcnt(0)
	v_mov_b32_e32 v2, 0x20160
	ds_read2_b32 v[4:5], v2 offset1:1
	ds_read_b32 v6, v2 offset:8
	v_readlane_b32 s100, v254, 8
	v_readlane_b32 s101, v254, 9
	v_mov_b32_e32 v3, 1
	v_mov_b32_e32 v11, 0
	v_mov_b32_e32 v8, s100
	v_mov_b32_e32 v9, s101
	global_atomic_add v10, v[8:9], v3, off sc0
	s_waitcnt lgkmcnt(0)
	v_add_u32_e32 v7, 1, v6
	ds_write_b32 v2, v7 offset:8
	v_mul_lo_u32 v4, v4, v7
	v_mul_lo_u32 v5, v5, v7
	s_waitcnt vmcnt(0)
	buffer_inv sc1
	v_add_u32_e32 v10, 1, v10
	v_cmp_eq_u32_e32 vcc, v10, v4
	s_cbranch_vccz .Lxb7_follow
	buffer_wbl2 sc1
	v_readlane_b32 s100, v254, 12
	v_readlane_b32 s101, v254, 13
	s_nop 1
	v_mov_b32_e32 v8, s100
	v_mov_b32_e32 v9, s101
	s_waitcnt vmcnt(0)
	global_atomic_add v10, v[8:9], v3, off sc0
	v_readlane_b32 s100, v254, 14
	v_readlane_b32 s101, v254, 15
	s_nop 1
	v_mov_b32_e32 v8, s100
	v_mov_b32_e32 v9, s101
	s_waitcnt vmcnt(0)
	v_add_u32_e32 v10, 1, v10
	v_cmp_eq_u32_e32 vcc, v10, v5
	s_cbranch_vccz .Lxb7_wait
	global_atomic_add v[8:9], v3, off
	s_branch .Lxb7_fin

.LBB0_842:
	s_add_i32 s6, s17, 8
	s_cmp_ge_i32 s6, s51
	s_cbranch_scc1 .LBB0_896
	s_waitcnt vmcnt(0)
	s_waitcnt vmcnt(0) lgkmcnt(0)
	s_barrier
	s_mov_b64 s[4:5], exec
	v_readlane_b32 s8, v253, 0
	v_readlane_b32 s9, v253, 1
	s_and_b64 s[8:9], s[4:5], s[8:9]
	s_mov_b64 exec, s[8:9]
	s_cbranch_execz .LBB0_895
	s_waitcnt lgkmcnt(0)
	v_mov_b32_e32 v2, 0x20160
	ds_read2_b32 v[4:5], v2 offset1:1
	ds_read_b32 v6, v2 offset:8
	v_readlane_b32 s100, v254, 8
	v_readlane_b32 s101, v254, 9
	v_mov_b32_e32 v3, 1
	v_mov_b32_e32 v11, 0
	v_mov_b32_e32 v8, s100
	v_mov_b32_e32 v9, s101
	global_atomic_add v10, v[8:9], v3, off sc0
	s_waitcnt lgkmcnt(0)
	v_add_u32_e32 v7, 1, v6
	ds_write_b32 v2, v7 offset:8
	v_mul_lo_u32 v4, v4, v7
	v_mul_lo_u32 v5, v5, v7
	s_waitcnt vmcnt(0)
	buffer_inv sc1
	v_add_u32_e32 v10, 1, v10
	v_cmp_eq_u32_e32 vcc, v10, v4
	s_cbranch_vccz .Lxb8_follow
	buffer_wbl2 sc1
	v_readlane_b32 s100, v254, 12
	v_readlane_b32 s101, v254, 13
	s_nop 1
	v_mov_b32_e32 v8, s100
	v_mov_b32_e32 v9, s101
	s_waitcnt vmcnt(0)
	global_atomic_add v10, v[8:9], v3, off sc0
	v_readlane_b32 s100, v254, 14
	v_readlane_b32 s101, v254, 15
	s_nop 1
	v_mov_b32_e32 v8, s100
	v_mov_b32_e32 v9, s101
	s_waitcnt vmcnt(0)
	v_add_u32_e32 v10, 1, v10
	v_cmp_eq_u32_e32 vcc, v10, v5
	s_cbranch_vccz .Lxb8_wait
	global_atomic_add v[8:9], v3, off
	s_branch .Lxb8_fin

.LBB0_908:
	s_add_i32 s7, s17, 9
	s_cmp_ge_i32 s7, s51
	s_cbranch_scc1 .LBB0_962
	s_waitcnt vmcnt(0)
	s_waitcnt vmcnt(0) lgkmcnt(0)
	s_barrier
	s_mov_b64 s[4:5], exec
	v_readlane_b32 s8, v253, 0
	v_readlane_b32 s9, v253, 1
	s_and_b64 s[8:9], s[4:5], s[8:9]
	s_mov_b64 exec, s[8:9]
	s_cbranch_execz .LBB0_961
	s_waitcnt lgkmcnt(0)
	v_mov_b32_e32 v2, 0x20160
	ds_read2_b32 v[4:5], v2 offset1:1
	ds_read_b32 v6, v2 offset:8
	v_readlane_b32 s100, v254, 8
	v_readlane_b32 s101, v254, 9
	v_mov_b32_e32 v3, 1
	v_mov_b32_e32 v11, 0
	v_mov_b32_e32 v8, s100
	v_mov_b32_e32 v9, s101
	global_atomic_add v10, v[8:9], v3, off sc0
	s_waitcnt lgkmcnt(0)
	v_add_u32_e32 v7, 1, v6
	ds_write_b32 v2, v7 offset:8
	v_mul_lo_u32 v4, v4, v7
	v_mul_lo_u32 v5, v5, v7
	s_waitcnt vmcnt(0)
	buffer_inv sc1
	v_add_u32_e32 v10, 1, v10
	v_cmp_eq_u32_e32 vcc, v10, v4
	s_cbranch_vccz .Lxb9_follow
	buffer_wbl2 sc1
	v_readlane_b32 s100, v254, 12
	v_readlane_b32 s101, v254, 13
	s_nop 1
	v_mov_b32_e32 v8, s100
	v_mov_b32_e32 v9, s101
	s_waitcnt vmcnt(0)
	global_atomic_add v10, v[8:9], v3, off sc0
	v_readlane_b32 s100, v254, 14
	v_readlane_b32 s101, v254, 15
	s_nop 1
	v_mov_b32_e32 v8, s100
	v_mov_b32_e32 v9, s101
	s_waitcnt vmcnt(0)
	v_add_u32_e32 v10, 1, v10
	v_cmp_eq_u32_e32 vcc, v10, v5
	s_cbranch_vccz .Lxb9_wait
	global_atomic_add v[8:9], v3, off
	s_branch .Lxb9_fin

.LBB0_1020:
	s_add_i32 s6, s17, 10
	s_cmp_ge_i32 s6, s51
	s_cbranch_scc1 .LBB0_1074
	s_waitcnt vmcnt(0)
	s_waitcnt vmcnt(0) lgkmcnt(0)
	s_barrier
	s_mov_b64 s[4:5], exec
	v_readlane_b32 s8, v253, 0
	v_readlane_b32 s9, v253, 1
	s_and_b64 s[8:9], s[4:5], s[8:9]
	s_mov_b64 exec, s[8:9]
	s_cbranch_execz .LBB0_1073
	s_waitcnt lgkmcnt(0)
	v_mov_b32_e32 v2, 0x20160
	ds_read2_b32 v[4:5], v2 offset1:1
	ds_read_b32 v6, v2 offset:8
	v_readlane_b32 s100, v254, 8
	v_readlane_b32 s101, v254, 9
	v_mov_b32_e32 v3, 1
	v_mov_b32_e32 v11, 0
	v_mov_b32_e32 v8, s100
	v_mov_b32_e32 v9, s101
	global_atomic_add v10, v[8:9], v3, off sc0
	s_waitcnt lgkmcnt(0)
	v_add_u32_e32 v7, 1, v6
	ds_write_b32 v2, v7 offset:8
	v_mul_lo_u32 v4, v4, v7
	v_mul_lo_u32 v5, v5, v7
	s_waitcnt vmcnt(0)
	buffer_inv sc1
	v_add_u32_e32 v10, 1, v10
	v_cmp_eq_u32_e32 vcc, v10, v4
	s_cbranch_vccz .Lxb10_follow
	buffer_wbl2 sc1
	v_readlane_b32 s100, v254, 12
	v_readlane_b32 s101, v254, 13
	s_nop 1
	v_mov_b32_e32 v8, s100
	v_mov_b32_e32 v9, s101
	s_waitcnt vmcnt(0)
	global_atomic_add v10, v[8:9], v3, off sc0
	v_readlane_b32 s100, v254, 14
	v_readlane_b32 s101, v254, 15
	s_nop 1
	v_mov_b32_e32 v8, s100
	v_mov_b32_e32 v9, s101
	s_waitcnt vmcnt(0)
	v_add_u32_e32 v10, 1, v10
	v_cmp_eq_u32_e32 vcc, v10, v5
	s_cbranch_vccz .Lxb10_wait
	global_atomic_add v[8:9], v3, off
	s_branch .Lxb10_fin

.LBB0_1088:
	s_or_b64 exec, exec, s[4:5]
	s_add_i32 s6, s17, 11
	s_cmp_ge_i32 s6, s51
	s_cbranch_scc1 .LBB0_1142
	s_waitcnt vmcnt(0)
	s_waitcnt vmcnt(0) lgkmcnt(0)
	s_barrier
	s_mov_b64 s[4:5], exec
	v_readlane_b32 s8, v253, 0
	v_readlane_b32 s9, v253, 1
	s_and_b64 s[8:9], s[4:5], s[8:9]
	s_mov_b64 exec, s[8:9]
	s_cbranch_execz .LBB0_1141
	s_waitcnt lgkmcnt(0)
	v_mov_b32_e32 v2, 0x20160
	ds_read2_b32 v[4:5], v2 offset1:1
	ds_read_b32 v6, v2 offset:8
	v_readlane_b32 s100, v254, 8
	v_readlane_b32 s101, v254, 9
	v_mov_b32_e32 v3, 1
	v_mov_b32_e32 v11, 0
	v_mov_b32_e32 v8, s100
	v_mov_b32_e32 v9, s101
	global_atomic_add v10, v[8:9], v3, off sc0
	s_waitcnt lgkmcnt(0)
	v_add_u32_e32 v7, 1, v6
	ds_write_b32 v2, v7 offset:8
	v_mul_lo_u32 v4, v4, v7
	v_mul_lo_u32 v5, v5, v7
	s_waitcnt vmcnt(0)
	buffer_inv sc1
	v_add_u32_e32 v10, 1, v10
	v_cmp_eq_u32_e32 vcc, v10, v4
	s_cbranch_vccz .Lxb11_follow
	buffer_wbl2 sc1
	v_readlane_b32 s100, v254, 12
	v_readlane_b32 s101, v254, 13
	s_nop 1
	v_mov_b32_e32 v8, s100
	v_mov_b32_e32 v9, s101
	s_waitcnt vmcnt(0)
	global_atomic_add v10, v[8:9], v3, off sc0
	v_readlane_b32 s100, v254, 14
	v_readlane_b32 s101, v254, 15
	s_nop 1
	v_mov_b32_e32 v8, s100
	v_mov_b32_e32 v9, s101
	s_waitcnt vmcnt(0)
	v_add_u32_e32 v10, 1, v10
	v_cmp_eq_u32_e32 vcc, v10, v5
	s_cbranch_vccz .Lxb11_wait
	global_atomic_add v[8:9], v3, off
	s_branch .Lxb11_fin
